# pooling phase: interior 64-token blocks use a hand-written body with the row loads software-pipelined four tokens ahead (was one load-wait-use round trip per row)
# speedup vs baseline: 1.0069x; 1.0038x over previous
; #define POOL_ACC(V_, sg) do { s0 += sg bflo(V_.x); s1 += sg bfhi(V_.x); s2 += sg bflo(V_.y); s3 += sg bfhi(V_.y); s4 += sg bflo(V_.z); s5 += sg bfhi(V_.z); s6 += sg bflo(V_.w); s7 += sg bfhi(V_.w); } while (0)
; __device__ __forceinline__ void pool_phase(const bf16_t* zp, bf16_t* mixed, const int wave_s) {
;     ...
;     for (int r = blockIdx.x * 8 + wave_s; r < MTOK / 64; r += gridDim.x * 8) {
;         const int tok_base = r * 64, S = tok_base < NPROMPT ? SEQP : SEQS, pos0 = tok_base & (S - 1);
;         const bf16_t* zs = zp + (size_t)(tok_base - pos0) * 512 + c0;
;         bf16_t* ms = mixed + (size_t)(tok_base - pos0) * DM + 512 + c0;
;         float s0 = 0.f, s1 = 0.f, s2 = 0.f, s3 = 0.f, s4 = 0.f, s5 = 0.f, s6 = 0.f, s7 = 0.f;
;     ...
; #pragma unroll
;         for (int d = -8; d < 8; ++d) { const int j = pos0 + d; if (d >= -half && d < half && j >= 0 && j < S) { const u32x4 w = *(const u32x4*)(zs + (size_t)j * 512); POOL_ACC(w, +); } }
.LBB0_312:
	s_lshl_b32 s3, s23, 6
	s_cmpk_lt_i32 s23, 0x400
	s_cselect_b32 s40, s34, 0x2000
	s_add_i32 s41, s40, -1
	s_and_b32 s2, s41, s3
	s_cmp_eq_u32 s2, 0
	s_cbranch_scc1 .Lpool_slow
	s_add_i32 s26, s2, 64
	s_cmp_eq_u32 s26, s40
	s_cbranch_scc1 .Lpool_slow
	s_add_i32 s25, s3, -8
	s_lshl_b32 s25, s25, 10
	s_add_u32 s28, s80, s25
	s_addc_u32 s29, s81, 0
	s_add_u32 s28, s28, 0x19a00000
	s_addc_u32 s29, s29, 0
	s_lshl_b32 s25, s3, 11
	s_add_u32 s30, s80, s25
	s_addc_u32 s31, s81, 0
	s_add_u32 s30, s30, 0x21a00400
	s_addc_u32 s31, s31, 0
	s_mov_b64 s[40:41], s[28:29]
	global_load_dwordx4 v[160:163], v0, s[40:41]
	global_load_dwordx4 v[168:171], v0, s[40:41] offset:1024
	global_load_dwordx4 v[172:175], v0, s[40:41] offset:2048
	global_load_dwordx4 v[180:183], v0, s[40:41] offset:3072
	s_add_u32 s40, s40, 0x1000
	s_addc_u32 s41, s41, 0
	global_load_dwordx4 v[184:187], v0, s[40:41]
	global_load_dwordx4 v[188:191], v0, s[40:41] offset:1024
	global_load_dwordx4 v[246:249], v0, s[40:41] offset:2048
	global_load_dwordx4 v[250:253], v0, s[40:41] offset:3072
	s_add_u32 s40, s40, 0x1000
	s_addc_u32 s41, s41, 0
	v_lshlrev_b32_e32 v4, 10, v26
	v_add_u32_e32 v237, 0x2000, v0
	v_add_u32_e32 v36, v237, v4
	v_sub_u32_e32 v37, v237, v4
	v_ffbl_b32_e32 v6, v26
	v_sub_u32_e32 v6, 0x7e, v6
	v_lshlrev_b32_e32 v228, 23, v6
	v_mov_b32_e32 v8, 0
	v_mov_b32_e32 v9, 0
	v_mov_b32_e32 v10, 0
	v_mov_b32_e32 v11, 0
	v_mov_b32_e32 v12, 0
	v_mov_b32_e32 v13, 0
	v_mov_b32_e32 v14, 0
	v_mov_b32_e32 v15, 0
	s_waitcnt vmcnt(7)
	s_mov_b32 exec_lo, 0
	s_mov_b32 exec_hi, 0xffff0000
	v_lshlrev_b32_e32 v4, 16, v160
	v_and_b32_e32 v6, 0xffff0000, v160
	v_lshlrev_b32_e32 v7, 16, v161
	v_and_b32_e32 v24, 0xffff0000, v161
	v_lshlrev_b32_e32 v25, 16, v162
	v_and_b32_e32 v164, 0xffff0000, v162
	v_lshlrev_b32_e32 v165, 16, v163
	v_and_b32_e32 v192, 0xffff0000, v163
	v_add_f32_e32 v8, v8, v4
	v_add_f32_e32 v9, v9, v6
	v_add_f32_e32 v10, v10, v7
	v_add_f32_e32 v11, v11, v24
	v_add_f32_e32 v12, v12, v25
	v_add_f32_e32 v13, v13, v164
	v_add_f32_e32 v14, v14, v165
	v_add_f32_e32 v15, v15, v192
	s_waitcnt vmcnt(6)
	v_lshlrev_b32_e32 v4, 16, v168
	v_and_b32_e32 v6, 0xffff0000, v168
	v_lshlrev_b32_e32 v7, 16, v169
	v_and_b32_e32 v24, 0xffff0000, v169
	v_lshlrev_b32_e32 v25, 16, v170
	v_and_b32_e32 v164, 0xffff0000, v170
	v_lshlrev_b32_e32 v165, 16, v171
	v_and_b32_e32 v192, 0xffff0000, v171
	v_add_f32_e32 v8, v8, v4
	v_add_f32_e32 v9, v9, v6
	v_add_f32_e32 v10, v10, v7
	v_add_f32_e32 v11, v11, v24
	v_add_f32_e32 v12, v12, v25
	v_add_f32_e32 v13, v13, v164
	v_add_f32_e32 v14, v14, v165
	v_add_f32_e32 v15, v15, v192
	s_waitcnt vmcnt(5)
	v_lshlrev_b32_e32 v4, 16, v172
	v_and_b32_e32 v6, 0xffff0000, v172
	v_lshlrev_b32_e32 v7, 16, v173
	v_and_b32_e32 v24, 0xffff0000, v173
	v_lshlrev_b32_e32 v25, 16, v174
	v_and_b32_e32 v164, 0xffff0000, v174
	v_lshlrev_b32_e32 v165, 16, v175
	v_and_b32_e32 v192, 0xffff0000, v175
	v_add_f32_e32 v8, v8, v4
	v_add_f32_e32 v9, v9, v6
	v_add_f32_e32 v10, v10, v7
	v_add_f32_e32 v11, v11, v24
	v_add_f32_e32 v12, v12, v25
	v_add_f32_e32 v13, v13, v164
	v_add_f32_e32 v14, v14, v165
	v_add_f32_e32 v15, v15, v192
	s_waitcnt vmcnt(4)
	v_lshlrev_b32_e32 v4, 16, v180
	v_and_b32_e32 v6, 0xffff0000, v180
	v_lshlrev_b32_e32 v7, 16, v181
	v_and_b32_e32 v24, 0xffff0000, v181
	v_lshlrev_b32_e32 v25, 16, v182
	v_and_b32_e32 v164, 0xffff0000, v182
	v_lshlrev_b32_e32 v165, 16, v183
	v_and_b32_e32 v192, 0xffff0000, v183
	v_add_f32_e32 v8, v8, v4
	v_add_f32_e32 v9, v9, v6
	v_add_f32_e32 v10, v10, v7
	v_add_f32_e32 v11, v11, v24
	v_add_f32_e32 v12, v12, v25
	v_add_f32_e32 v13, v13, v164
	v_add_f32_e32 v14, v14, v165
	v_add_f32_e32 v15, v15, v192
	s_waitcnt vmcnt(3)
	s_mov_b32 exec_lo, 0
	s_mov_b32 exec_hi, 0xffffffff
	v_lshlrev_b32_e32 v4, 16, v184
	v_and_b32_e32 v6, 0xffff0000, v184
	v_lshlrev_b32_e32 v7, 16, v185
	v_and_b32_e32 v24, 0xffff0000, v185
	v_lshlrev_b32_e32 v25, 16, v186
	v_and_b32_e32 v164, 0xffff0000, v186
	v_lshlrev_b32_e32 v165, 16, v187
	v_and_b32_e32 v192, 0xffff0000, v187
	v_add_f32_e32 v8, v8, v4
	v_add_f32_e32 v9, v9, v6
	v_add_f32_e32 v10, v10, v7
	v_add_f32_e32 v11, v11, v24
	v_add_f32_e32 v12, v12, v25
	v_add_f32_e32 v13, v13, v164
	v_add_f32_e32 v14, v14, v165
	v_add_f32_e32 v15, v15, v192
	s_waitcnt vmcnt(2)
	v_lshlrev_b32_e32 v4, 16, v188
	v_and_b32_e32 v6, 0xffff0000, v188
	v_lshlrev_b32_e32 v7, 16, v189
	v_and_b32_e32 v24, 0xffff0000, v189
	v_lshlrev_b32_e32 v25, 16, v190
	v_and_b32_e32 v164, 0xffff0000, v190
	v_lshlrev_b32_e32 v165, 16, v191
	v_and_b32_e32 v192, 0xffff0000, v191
	v_add_f32_e32 v8, v8, v4
	v_add_f32_e32 v9, v9, v6
	v_add_f32_e32 v10, v10, v7
	v_add_f32_e32 v11, v11, v24
	v_add_f32_e32 v12, v12, v25
	v_add_f32_e32 v13, v13, v164
	v_add_f32_e32 v14, v14, v165
	v_add_f32_e32 v15, v15, v192
	s_waitcnt vmcnt(1)
	s_mov_b32 exec_lo, 0xffff0000
	s_mov_b32 exec_hi, 0xffffffff
	v_lshlrev_b32_e32 v4, 16, v246
	v_and_b32_e32 v6, 0xffff0000, v246
	v_lshlrev_b32_e32 v7, 16, v247
	v_and_b32_e32 v24, 0xffff0000, v247
	v_lshlrev_b32_e32 v25, 16, v248
	v_and_b32_e32 v164, 0xffff0000, v248
	v_lshlrev_b32_e32 v165, 16, v249
	v_and_b32_e32 v192, 0xffff0000, v249
	v_add_f32_e32 v8, v8, v4
	v_add_f32_e32 v9, v9, v6
	v_add_f32_e32 v10, v10, v7
	v_add_f32_e32 v11, v11, v24
	v_add_f32_e32 v12, v12, v25
	v_add_f32_e32 v13, v13, v164
	v_add_f32_e32 v14, v14, v165
	v_add_f32_e32 v15, v15, v192
	s_waitcnt vmcnt(0)
; __device__ __forceinline__ unsigned cvt_pk_bf16(float lo, float hi) { unsigned r; asm volatile("v_cvt_pk_bf16_f32 %0, %1, %2" : "=v"(r) : "v"(lo), "v"(hi)); return r; }
; __device__ __forceinline__ float bflo(unsigned w) { return __uint_as_float(w << 16); }
; __device__ __forceinline__ float bfhi(unsigned w) { return __uint_as_float(w & 0xffff0000u); }
; #define POOL_ACC(V_, sg) do { s0 += sg bflo(V_.x); s1 += sg bfhi(V_.x); s2 += sg bflo(V_.y); s3 += sg bfhi(V_.y); s4 += sg bflo(V_.z); s5 += sg bfhi(V_.z); s6 += sg bflo(V_.w); s7 += sg bfhi(V_.w); } while (0)
; __device__ __forceinline__ void pool_phase(const bf16_t* zp, bf16_t* mixed, const int wave_s) {
;     ...
;         for (int d = -8; d < 8; ++d) { const int j = pos0 + d; if (d >= -half && d < half && j >= 0 && j < S) { const u32x4 w = *(const u32x4*)(zs + (size_t)j * 512); POOL_ACC(w, +); } }
; #pragma unroll 4
;         for (int i = 0; i < 64; ++i) {
;             const int sp = pos0 + i, lo = max(sp - half, 0), hi = min(sp + half - 1, S - 1);
;             const float ic = 1.0f / (float)(hi - lo + 1);
;             const u32x4 w = *(const u32x4*)(zs + (size_t)sp * 512);
;             u32x4 o;
;             o.x = cvt_pk_bf16(s0 * ic - bflo(w.x), s1 * ic - bfhi(w.x)); o.y = cvt_pk_bf16(s2 * ic - bflo(w.y), s3 * ic - bfhi(w.y));
;             o.z = cvt_pk_bf16(s4 * ic - bflo(w.z), s5 * ic - bfhi(w.z)); o.w = cvt_pk_bf16(s6 * ic - bflo(w.w), s7 * ic - bfhi(w.w));
;             *(u32x4*)(ms + (size_t)sp * DM) = o;
;             const int jn = sp + half, jo = sp - half;
;             if (jn < S) { const u32x4 wn = *(const u32x4*)(zs + (size_t)jn * 512); POOL_ACC(wn, +); }
;             if (jo >= 0) { const u32x4 wo = *(const u32x4*)(zs + (size_t)jo * 512); POOL_ACC(wo, -); }
	s_mov_b32 exec_lo, 0xffffffff
	s_mov_b32 exec_hi, 0xffffffff
	v_lshlrev_b32_e32 v4, 16, v250
	v_and_b32_e32 v6, 0xffff0000, v250
	v_lshlrev_b32_e32 v7, 16, v251
	v_and_b32_e32 v24, 0xffff0000, v251
	v_lshlrev_b32_e32 v25, 16, v252
	v_and_b32_e32 v164, 0xffff0000, v252
	v_lshlrev_b32_e32 v165, 16, v253
	v_and_b32_e32 v192, 0xffff0000, v253
	v_add_f32_e32 v8, v8, v4
	v_add_f32_e32 v9, v9, v6
	v_add_f32_e32 v10, v10, v7
	v_add_f32_e32 v11, v11, v24
	v_add_f32_e32 v12, v12, v25
	v_add_f32_e32 v13, v13, v164
	v_add_f32_e32 v14, v14, v165
	v_add_f32_e32 v15, v15, v192
	global_load_dwordx4 v[160:163], v0, s[40:41]
	global_load_dwordx4 v[168:171], v0, s[40:41] offset:1024
	global_load_dwordx4 v[172:175], v0, s[40:41] offset:2048
	global_load_dwordx4 v[180:183], v0, s[40:41] offset:3072
	s_add_u32 s40, s40, 0x1000
	s_addc_u32 s41, s41, 0
	global_load_dwordx4 v[184:187], v0, s[40:41]
	global_load_dwordx4 v[188:191], v0, s[40:41] offset:1024
	global_load_dwordx4 v[246:249], v0, s[40:41] offset:2048
	global_load_dwordx4 v[250:253], v0, s[40:41] offset:3072
	s_waitcnt vmcnt(7)
	v_lshlrev_b32_e32 v4, 16, v160
	v_and_b32_e32 v6, 0xffff0000, v160
	v_lshlrev_b32_e32 v7, 16, v161
	v_and_b32_e32 v24, 0xffff0000, v161
	v_lshlrev_b32_e32 v25, 16, v162
	v_and_b32_e32 v164, 0xffff0000, v162
	v_lshlrev_b32_e32 v165, 16, v163
	v_and_b32_e32 v192, 0xffff0000, v163
	v_add_f32_e32 v8, v8, v4
	v_add_f32_e32 v9, v9, v6
	v_add_f32_e32 v10, v10, v7
	v_add_f32_e32 v11, v11, v24
	v_add_f32_e32 v12, v12, v25
	v_add_f32_e32 v13, v13, v164
	v_add_f32_e32 v14, v14, v165
	v_add_f32_e32 v15, v15, v192
	s_waitcnt vmcnt(6)
	s_mov_b32 exec_lo, 0xffff0000
	s_mov_b32 exec_hi, 0xffffffff
	v_lshlrev_b32_e32 v4, 16, v168
	v_and_b32_e32 v6, 0xffff0000, v168
	v_lshlrev_b32_e32 v7, 16, v169
	v_and_b32_e32 v24, 0xffff0000, v169
	v_lshlrev_b32_e32 v25, 16, v170
	v_and_b32_e32 v164, 0xffff0000, v170
	v_lshlrev_b32_e32 v165, 16, v171
	v_and_b32_e32 v192, 0xffff0000, v171
	v_add_f32_e32 v8, v8, v4
	v_add_f32_e32 v9, v9, v6
	v_add_f32_e32 v10, v10, v7
	v_add_f32_e32 v11, v11, v24
	v_add_f32_e32 v12, v12, v25
	v_add_f32_e32 v13, v13, v164
	v_add_f32_e32 v14, v14, v165
	v_add_f32_e32 v15, v15, v192
	s_waitcnt vmcnt(5)
	s_mov_b32 exec_lo, 0
	s_mov_b32 exec_hi, 0xffffffff
	v_lshlrev_b32_e32 v4, 16, v172
	v_and_b32_e32 v6, 0xffff0000, v172
	v_lshlrev_b32_e32 v7, 16, v173
	v_and_b32_e32 v24, 0xffff0000, v173
	v_lshlrev_b32_e32 v25, 16, v174
	v_and_b32_e32 v164, 0xffff0000, v174
	v_lshlrev_b32_e32 v165, 16, v175
	v_and_b32_e32 v192, 0xffff0000, v175
	v_add_f32_e32 v8, v8, v4
	v_add_f32_e32 v9, v9, v6
	v_add_f32_e32 v10, v10, v7
	v_add_f32_e32 v11, v11, v24
	v_add_f32_e32 v12, v12, v25
	v_add_f32_e32 v13, v13, v164
	v_add_f32_e32 v14, v14, v165
	v_add_f32_e32 v15, v15, v192
	s_waitcnt vmcnt(4)
	v_lshlrev_b32_e32 v4, 16, v180
	v_and_b32_e32 v6, 0xffff0000, v180
	v_lshlrev_b32_e32 v7, 16, v181
	v_and_b32_e32 v24, 0xffff0000, v181
	v_lshlrev_b32_e32 v25, 16, v182
	v_and_b32_e32 v164, 0xffff0000, v182
	v_lshlrev_b32_e32 v165, 16, v183
	v_and_b32_e32 v192, 0xffff0000, v183
	v_add_f32_e32 v8, v8, v4
	v_add_f32_e32 v9, v9, v6
	v_add_f32_e32 v10, v10, v7
	v_add_f32_e32 v11, v11, v24
	v_add_f32_e32 v12, v12, v25
	v_add_f32_e32 v13, v13, v164
	v_add_f32_e32 v14, v14, v165
	v_add_f32_e32 v15, v15, v192
	s_waitcnt vmcnt(3)
	s_mov_b32 exec_lo, 0
	s_mov_b32 exec_hi, 0xffff0000
	v_lshlrev_b32_e32 v4, 16, v184
	v_and_b32_e32 v6, 0xffff0000, v184
	v_lshlrev_b32_e32 v7, 16, v185
	v_and_b32_e32 v24, 0xffff0000, v185
	v_lshlrev_b32_e32 v25, 16, v186
	v_and_b32_e32 v164, 0xffff0000, v186
	v_lshlrev_b32_e32 v165, 16, v187
	v_and_b32_e32 v192, 0xffff0000, v187
	v_add_f32_e32 v8, v8, v4
	v_add_f32_e32 v9, v9, v6
	v_add_f32_e32 v10, v10, v7
	v_add_f32_e32 v11, v11, v24
	v_add_f32_e32 v12, v12, v25
	v_add_f32_e32 v13, v13, v164
	v_add_f32_e32 v14, v14, v165
	v_add_f32_e32 v15, v15, v192
	s_waitcnt vmcnt(2)
	v_lshlrev_b32_e32 v4, 16, v188
	v_and_b32_e32 v6, 0xffff0000, v188
	v_lshlrev_b32_e32 v7, 16, v189
	v_and_b32_e32 v24, 0xffff0000, v189
	v_lshlrev_b32_e32 v25, 16, v190
	v_and_b32_e32 v164, 0xffff0000, v190
	v_lshlrev_b32_e32 v165, 16, v191
	v_and_b32_e32 v192, 0xffff0000, v191
	v_add_f32_e32 v8, v8, v4
	v_add_f32_e32 v9, v9, v6
	v_add_f32_e32 v10, v10, v7
	v_add_f32_e32 v11, v11, v24
	v_add_f32_e32 v12, v12, v25
	v_add_f32_e32 v13, v13, v164
	v_add_f32_e32 v14, v14, v165
	v_add_f32_e32 v15, v15, v192
	s_waitcnt vmcnt(1)
	v_lshlrev_b32_e32 v4, 16, v246
	v_and_b32_e32 v6, 0xffff0000, v246
	v_lshlrev_b32_e32 v7, 16, v247
	v_and_b32_e32 v24, 0xffff0000, v247
	v_lshlrev_b32_e32 v25, 16, v248
	v_and_b32_e32 v164, 0xffff0000, v248
	v_lshlrev_b32_e32 v165, 16, v249
	v_and_b32_e32 v192, 0xffff0000, v249
	v_add_f32_e32 v8, v8, v4
	v_add_f32_e32 v9, v9, v6
	v_add_f32_e32 v10, v10, v7
	v_add_f32_e32 v11, v11, v24
	v_add_f32_e32 v12, v12, v25
	v_add_f32_e32 v13, v13, v164
	v_add_f32_e32 v14, v14, v165
	v_add_f32_e32 v15, v15, v192
	s_waitcnt vmcnt(0)
	v_lshlrev_b32_e32 v4, 16, v250
	v_and_b32_e32 v6, 0xffff0000, v250
	v_lshlrev_b32_e32 v7, 16, v251
	v_and_b32_e32 v24, 0xffff0000, v251
	v_lshlrev_b32_e32 v25, 16, v252
	v_and_b32_e32 v164, 0xffff0000, v252
	v_lshlrev_b32_e32 v165, 16, v253
	v_and_b32_e32 v192, 0xffff0000, v253
	v_add_f32_e32 v8, v8, v4
	v_add_f32_e32 v9, v9, v6
	v_add_f32_e32 v10, v10, v7
	v_add_f32_e32 v11, v11, v24
	v_add_f32_e32 v12, v12, v25
	v_add_f32_e32 v13, v13, v164
	v_add_f32_e32 v14, v14, v165
	v_add_f32_e32 v15, v15, v192
	s_mov_b32 exec_lo, 0xffffffff
	s_mov_b32 exec_hi, 0xffffffff
	global_load_dwordx4 v[160:163], v237, s[28:29]
	global_load_dwordx4 v[168:171], v36, s[28:29]
	global_load_dwordx4 v[172:175], v37, s[28:29]
	global_load_dwordx4 v[180:183], v237, s[28:29] offset:1024
	global_load_dwordx4 v[184:187], v36, s[28:29] offset:1024
	global_load_dwordx4 v[188:191], v37, s[28:29] offset:1024
	global_load_dwordx4 v[246:249], v237, s[28:29] offset:2048
	global_load_dwordx4 v[250:253], v36, s[28:29] offset:2048
	global_load_dwordx4 v[20:23], v37, s[28:29] offset:2048
	global_load_dwordx4 v[28:31], v237, s[28:29] offset:3072
	global_load_dwordx4 v[32:35], v36, s[28:29] offset:3072
	global_load_dwordx4 v[16:19], v37, s[28:29] offset:3072
	s_add_u32 s28, s28, 0x1000
	s_addc_u32 s29, s29, 0
	s_mov_b32 s25, 0
; __device__ __forceinline__ unsigned cvt_pk_bf16(float lo, float hi) { unsigned r; asm volatile("v_cvt_pk_bf16_f32 %0, %1, %2" : "=v"(r) : "v"(lo), "v"(hi)); return r; }
; __device__ __forceinline__ float bflo(unsigned w) { return __uint_as_float(w << 16); }
; __device__ __forceinline__ float bfhi(unsigned w) { return __uint_as_float(w & 0xffff0000u); }
; #define POOL_ACC(V_, sg) do { s0 += sg bflo(V_.x); s1 += sg bfhi(V_.x); s2 += sg bflo(V_.y); s3 += sg bfhi(V_.y); s4 += sg bflo(V_.z); s5 += sg bfhi(V_.z); s6 += sg bflo(V_.w); s7 += sg bfhi(V_.w); } while (0)
; __device__ __forceinline__ void pool_phase(const bf16_t* zp, bf16_t* mixed, const int wave_s) {
;     ...
;         for (int i = 0; i < 64; ++i) {
;             const int sp = pos0 + i, lo = max(sp - half, 0), hi = min(sp + half - 1, S - 1);
;             const float ic = 1.0f / (float)(hi - lo + 1);
;             const u32x4 w = *(const u32x4*)(zs + (size_t)sp * 512);
;             u32x4 o;
;             o.x = cvt_pk_bf16(s0 * ic - bflo(w.x), s1 * ic - bfhi(w.x)); o.y = cvt_pk_bf16(s2 * ic - bflo(w.y), s3 * ic - bfhi(w.y));
;             o.z = cvt_pk_bf16(s4 * ic - bflo(w.z), s5 * ic - bfhi(w.z)); o.w = cvt_pk_bf16(s6 * ic - bflo(w.w), s7 * ic - bfhi(w.w));
;             *(u32x4*)(ms + (size_t)sp * DM) = o;
;             const int jn = sp + half, jo = sp - half;
;             if (jn < S) { const u32x4 wn = *(const u32x4*)(zs + (size_t)jn * 512); POOL_ACC(wn, +); }
;             if (jo >= 0) { const u32x4 wo = *(const u32x4*)(zs + (size_t)jo * 512); POOL_ACC(wo, -); }
.Lpool_loop:
	s_waitcnt vmcnt(9)
	v_lshlrev_b32_e32 v4, 16, v160
	v_and_b32_e32 v6, 0xffff0000, v160
	v_lshlrev_b32_e32 v7, 16, v161
	v_and_b32_e32 v24, 0xffff0000, v161
	v_lshlrev_b32_e32 v25, 16, v162
	v_and_b32_e32 v164, 0xffff0000, v162
	v_lshlrev_b32_e32 v165, 16, v163
	v_and_b32_e32 v192, 0xffff0000, v163
	v_fma_f32 v4, v8, v228, -v4
	v_fma_f32 v6, v9, v228, -v6
	v_fma_f32 v7, v10, v228, -v7
	v_fma_f32 v24, v11, v228, -v24
	v_fma_f32 v25, v12, v228, -v25
	v_fma_f32 v164, v13, v228, -v164
	v_fma_f32 v165, v14, v228, -v165
	v_fma_f32 v192, v15, v228, -v192
	v_cvt_pk_bf16_f32 v160, v4, v6
	v_cvt_pk_bf16_f32 v161, v7, v24
	v_cvt_pk_bf16_f32 v162, v25, v164
	v_cvt_pk_bf16_f32 v163, v165, v192
	global_store_dwordx4 v0, v[160:163], s[30:31]
	v_lshlrev_b32_e32 v4, 16, v168
	v_and_b32_e32 v6, 0xffff0000, v168
	v_lshlrev_b32_e32 v7, 16, v169
	v_and_b32_e32 v24, 0xffff0000, v169
	v_lshlrev_b32_e32 v25, 16, v170
	v_and_b32_e32 v164, 0xffff0000, v170
	v_lshlrev_b32_e32 v165, 16, v171
	v_and_b32_e32 v192, 0xffff0000, v171
	v_add_f32_e32 v8, v8, v4
	v_add_f32_e32 v9, v9, v6
	v_add_f32_e32 v10, v10, v7
	v_add_f32_e32 v11, v11, v24
	v_add_f32_e32 v12, v12, v25
	v_add_f32_e32 v13, v13, v164
	v_add_f32_e32 v14, v14, v165
	v_add_f32_e32 v15, v15, v192
	v_lshlrev_b32_e32 v4, 16, v172
	v_and_b32_e32 v6, 0xffff0000, v172
	v_lshlrev_b32_e32 v7, 16, v173
	v_and_b32_e32 v24, 0xffff0000, v173
	v_lshlrev_b32_e32 v25, 16, v174
	v_and_b32_e32 v164, 0xffff0000, v174
	v_lshlrev_b32_e32 v165, 16, v175
	v_and_b32_e32 v192, 0xffff0000, v175
	v_sub_f32_e32 v8, v8, v4
	v_sub_f32_e32 v9, v9, v6
	v_sub_f32_e32 v10, v10, v7
	v_sub_f32_e32 v11, v11, v24
	v_sub_f32_e32 v12, v12, v25
	v_sub_f32_e32 v13, v13, v164
	v_sub_f32_e32 v14, v14, v165
	v_sub_f32_e32 v15, v15, v192
	global_load_dwordx4 v[160:163], v237, s[28:29]
	global_load_dwordx4 v[168:171], v36, s[28:29]
	global_load_dwordx4 v[172:175], v37, s[28:29]
	s_waitcnt vmcnt(9)
	v_lshlrev_b32_e32 v4, 16, v180
	v_and_b32_e32 v6, 0xffff0000, v180
	v_lshlrev_b32_e32 v7, 16, v181
	v_and_b32_e32 v24, 0xffff0000, v181
	v_lshlrev_b32_e32 v25, 16, v182
	v_and_b32_e32 v164, 0xffff0000, v182
	v_lshlrev_b32_e32 v165, 16, v183
	v_and_b32_e32 v192, 0xffff0000, v183
	v_fma_f32 v4, v8, v228, -v4
	v_fma_f32 v6, v9, v228, -v6
	v_fma_f32 v7, v10, v228, -v7
	v_fma_f32 v24, v11, v228, -v24
	v_fma_f32 v25, v12, v228, -v25
	v_fma_f32 v164, v13, v228, -v164
	v_fma_f32 v165, v14, v228, -v165
	v_fma_f32 v192, v15, v228, -v192
	v_cvt_pk_bf16_f32 v180, v4, v6
	v_cvt_pk_bf16_f32 v181, v7, v24
	v_cvt_pk_bf16_f32 v182, v25, v164
	v_cvt_pk_bf16_f32 v183, v165, v192
	global_store_dwordx4 v0, v[180:183], s[30:31] offset:2048
	s_add_u32 s30, s30, 0x1000
	s_addc_u32 s31, s31, 0
	v_lshlrev_b32_e32 v4, 16, v184
	v_and_b32_e32 v6, 0xffff0000, v184
	v_lshlrev_b32_e32 v7, 16, v185
	v_and_b32_e32 v24, 0xffff0000, v185
	v_lshlrev_b32_e32 v25, 16, v186
	v_and_b32_e32 v164, 0xffff0000, v186
	v_lshlrev_b32_e32 v165, 16, v187
	v_and_b32_e32 v192, 0xffff0000, v187
	v_add_f32_e32 v8, v8, v4
	v_add_f32_e32 v9, v9, v6
	v_add_f32_e32 v10, v10, v7
	v_add_f32_e32 v11, v11, v24
	v_add_f32_e32 v12, v12, v25
	v_add_f32_e32 v13, v13, v164
	v_add_f32_e32 v14, v14, v165
	v_add_f32_e32 v15, v15, v192
	v_lshlrev_b32_e32 v4, 16, v188
	v_and_b32_e32 v6, 0xffff0000, v188
	v_lshlrev_b32_e32 v7, 16, v189
	v_and_b32_e32 v24, 0xffff0000, v189
	v_lshlrev_b32_e32 v25, 16, v190
	v_and_b32_e32 v164, 0xffff0000, v190
	v_lshlrev_b32_e32 v165, 16, v191
	v_and_b32_e32 v192, 0xffff0000, v191
	v_sub_f32_e32 v8, v8, v4
	v_sub_f32_e32 v9, v9, v6
	v_sub_f32_e32 v10, v10, v7
	v_sub_f32_e32 v11, v11, v24
	v_sub_f32_e32 v12, v12, v25
	v_sub_f32_e32 v13, v13, v164
	v_sub_f32_e32 v14, v14, v165
	v_sub_f32_e32 v15, v15, v192
	global_load_dwordx4 v[180:183], v237, s[28:29] offset:1024
	global_load_dwordx4 v[184:187], v36, s[28:29] offset:1024
	global_load_dwordx4 v[188:191], v37, s[28:29] offset:1024
	s_waitcnt vmcnt(9)
; __device__ __forceinline__ unsigned cvt_pk_bf16(float lo, float hi) { unsigned r; asm volatile("v_cvt_pk_bf16_f32 %0, %1, %2" : "=v"(r) : "v"(lo), "v"(hi)); return r; }
; __device__ __forceinline__ float bflo(unsigned w) { return __uint_as_float(w << 16); }
; __device__ __forceinline__ float bfhi(unsigned w) { return __uint_as_float(w & 0xffff0000u); }
; #define POOL_ACC(V_, sg) do { s0 += sg bflo(V_.x); s1 += sg bfhi(V_.x); s2 += sg bflo(V_.y); s3 += sg bfhi(V_.y); s4 += sg bflo(V_.z); s5 += sg bfhi(V_.z); s6 += sg bflo(V_.w); s7 += sg bfhi(V_.w); } while (0)
; __device__ __forceinline__ void pool_phase(const bf16_t* zp, bf16_t* mixed, const int wave_s) {
;     ...
;         const bf16_t* zs = zp + (size_t)(tok_base - pos0) * 512 + c0;
;         bf16_t* ms = mixed + (size_t)(tok_base - pos0) * DM + 512 + c0;
;         float s0 = 0.f, s1 = 0.f, s2 = 0.f, s3 = 0.f, s4 = 0.f, s5 = 0.f, s6 = 0.f, s7 = 0.f;
;     ...
; #pragma unroll
;         for (int d = -8; d < 8; ++d) { const int j = pos0 + d; if (d >= -half && d < half && j >= 0 && j < S) { const u32x4 w = *(const u32x4*)(zs + (size_t)j * 512); POOL_ACC(w, +); } }
;     ...
;         for (int i = 0; i < 64; ++i) {
;             const int sp = pos0 + i, lo = max(sp - half, 0), hi = min(sp + half - 1, S - 1);
;             const float ic = 1.0f / (float)(hi - lo + 1);
;             const u32x4 w = *(const u32x4*)(zs + (size_t)sp * 512);
;             u32x4 o;
;             o.x = cvt_pk_bf16(s0 * ic - bflo(w.x), s1 * ic - bfhi(w.x)); o.y = cvt_pk_bf16(s2 * ic - bflo(w.y), s3 * ic - bfhi(w.y));
;             o.z = cvt_pk_bf16(s4 * ic - bflo(w.z), s5 * ic - bfhi(w.z)); o.w = cvt_pk_bf16(s6 * ic - bflo(w.w), s7 * ic - bfhi(w.w));
;             *(u32x4*)(ms + (size_t)sp * DM) = o;
;             const int jn = sp + half, jo = sp - half;
;             if (jn < S) { const u32x4 wn = *(const u32x4*)(zs + (size_t)jn * 512); POOL_ACC(wn, +); }
;             if (jo >= 0) { const u32x4 wo = *(const u32x4*)(zs + (size_t)jo * 512); POOL_ACC(wo, -); }
	v_lshlrev_b32_e32 v4, 16, v246
	v_and_b32_e32 v6, 0xffff0000, v246
	v_lshlrev_b32_e32 v7, 16, v247
	v_and_b32_e32 v24, 0xffff0000, v247
	v_lshlrev_b32_e32 v25, 16, v248
	v_and_b32_e32 v164, 0xffff0000, v248
	v_lshlrev_b32_e32 v165, 16, v249
	v_and_b32_e32 v192, 0xffff0000, v249
	v_fma_f32 v4, v8, v228, -v4
	v_fma_f32 v6, v9, v228, -v6
	v_fma_f32 v7, v10, v228, -v7
	v_fma_f32 v24, v11, v228, -v24
	v_fma_f32 v25, v12, v228, -v25
	v_fma_f32 v164, v13, v228, -v164
	v_fma_f32 v165, v14, v228, -v165
	v_fma_f32 v192, v15, v228, -v192
	v_cvt_pk_bf16_f32 v246, v4, v6
	v_cvt_pk_bf16_f32 v247, v7, v24
	v_cvt_pk_bf16_f32 v248, v25, v164
	v_cvt_pk_bf16_f32 v249, v165, v192
	global_store_dwordx4 v0, v[246:249], s[30:31]
	v_lshlrev_b32_e32 v4, 16, v250
	v_and_b32_e32 v6, 0xffff0000, v250
	v_lshlrev_b32_e32 v7, 16, v251
	v_and_b32_e32 v24, 0xffff0000, v251
	v_lshlrev_b32_e32 v25, 16, v252
	v_and_b32_e32 v164, 0xffff0000, v252
	v_lshlrev_b32_e32 v165, 16, v253
	v_and_b32_e32 v192, 0xffff0000, v253
	v_add_f32_e32 v8, v8, v4
	v_add_f32_e32 v9, v9, v6
	v_add_f32_e32 v10, v10, v7
	v_add_f32_e32 v11, v11, v24
	v_add_f32_e32 v12, v12, v25
	v_add_f32_e32 v13, v13, v164
	v_add_f32_e32 v14, v14, v165
	v_add_f32_e32 v15, v15, v192
	v_lshlrev_b32_e32 v4, 16, v20
	v_and_b32_e32 v6, 0xffff0000, v20
	v_lshlrev_b32_e32 v7, 16, v21
	v_and_b32_e32 v24, 0xffff0000, v21
	v_lshlrev_b32_e32 v25, 16, v22
	v_and_b32_e32 v164, 0xffff0000, v22
	v_lshlrev_b32_e32 v165, 16, v23
	v_and_b32_e32 v192, 0xffff0000, v23
	v_sub_f32_e32 v8, v8, v4
	v_sub_f32_e32 v9, v9, v6
	v_sub_f32_e32 v10, v10, v7
	v_sub_f32_e32 v11, v11, v24
	v_sub_f32_e32 v12, v12, v25
	v_sub_f32_e32 v13, v13, v164
	v_sub_f32_e32 v14, v14, v165
	v_sub_f32_e32 v15, v15, v192
	global_load_dwordx4 v[246:249], v237, s[28:29] offset:2048
	global_load_dwordx4 v[250:253], v36, s[28:29] offset:2048
	global_load_dwordx4 v[20:23], v37, s[28:29] offset:2048
	s_waitcnt vmcnt(9)
	v_lshlrev_b32_e32 v4, 16, v28
	v_and_b32_e32 v6, 0xffff0000, v28
	v_lshlrev_b32_e32 v7, 16, v29
	v_and_b32_e32 v24, 0xffff0000, v29
	v_lshlrev_b32_e32 v25, 16, v30
	v_and_b32_e32 v164, 0xffff0000, v30
	v_lshlrev_b32_e32 v165, 16, v31
	v_and_b32_e32 v192, 0xffff0000, v31
	v_fma_f32 v4, v8, v228, -v4
	v_fma_f32 v6, v9, v228, -v6
	v_fma_f32 v7, v10, v228, -v7
	v_fma_f32 v24, v11, v228, -v24
	v_fma_f32 v25, v12, v228, -v25
	v_fma_f32 v164, v13, v228, -v164
	v_fma_f32 v165, v14, v228, -v165
	v_fma_f32 v192, v15, v228, -v192
	v_cvt_pk_bf16_f32 v28, v4, v6
	v_cvt_pk_bf16_f32 v29, v7, v24
	v_cvt_pk_bf16_f32 v30, v25, v164
	v_cvt_pk_bf16_f32 v31, v165, v192
	global_store_dwordx4 v0, v[28:31], s[30:31] offset:2048
	s_add_u32 s30, s30, 0x1000
	s_addc_u32 s31, s31, 0
	v_lshlrev_b32_e32 v4, 16, v32
	v_and_b32_e32 v6, 0xffff0000, v32
	v_lshlrev_b32_e32 v7, 16, v33
	v_and_b32_e32 v24, 0xffff0000, v33
	v_lshlrev_b32_e32 v25, 16, v34
	v_and_b32_e32 v164, 0xffff0000, v34
	v_lshlrev_b32_e32 v165, 16, v35
	v_and_b32_e32 v192, 0xffff0000, v35
	v_add_f32_e32 v8, v8, v4
	v_add_f32_e32 v9, v9, v6
	v_add_f32_e32 v10, v10, v7
	v_add_f32_e32 v11, v11, v24
	v_add_f32_e32 v12, v12, v25
	v_add_f32_e32 v13, v13, v164
	v_add_f32_e32 v14, v14, v165
	v_add_f32_e32 v15, v15, v192
	v_lshlrev_b32_e32 v4, 16, v16
	v_and_b32_e32 v6, 0xffff0000, v16
	v_lshlrev_b32_e32 v7, 16, v17
	v_and_b32_e32 v24, 0xffff0000, v17
	v_lshlrev_b32_e32 v25, 16, v18
	v_and_b32_e32 v164, 0xffff0000, v18
	v_lshlrev_b32_e32 v165, 16, v19
	v_and_b32_e32 v192, 0xffff0000, v19
	v_sub_f32_e32 v8, v8, v4
	v_sub_f32_e32 v9, v9, v6
	v_sub_f32_e32 v10, v10, v7
	v_sub_f32_e32 v11, v11, v24
	v_sub_f32_e32 v12, v12, v25
	v_sub_f32_e32 v13, v13, v164
	v_sub_f32_e32 v14, v14, v165
	v_sub_f32_e32 v15, v15, v192
	global_load_dwordx4 v[28:31], v237, s[28:29] offset:3072
	global_load_dwordx4 v[32:35], v36, s[28:29] offset:3072
	global_load_dwordx4 v[16:19], v37, s[28:29] offset:3072
	s_add_u32 s28, s28, 0x1000
	s_addc_u32 s29, s29, 0
	s_add_i32 s25, s25, 1
	s_cmp_lt_u32 s25, 16
	s_cbranch_scc1 .Lpool_loop
	s_waitcnt vmcnt(0)
	s_branch .LBB0_311
.Lpool_slow:
	s_sub_i32 s28, s3, s2
	s_ashr_i32 s29, s28, 31
	s_lshl_b64 s[28:29], s[28:29], 10
	s_add_i32 s26, s2, -8
	s_cmp_lt_u32 s26, s40
	v_lshl_add_u64 v[6:7], v[2:3], 0, s[28:29]
	s_cselect_b64 s[28:29], -1, 0
	v_mov_b32_e32 v4, v5
	s_and_b64 s[30:31], s[0:1], s[28:29]
	v_mov_b64_e32 v[14:15], v[4:5]
	v_mov_b64_e32 v[8:9], v[4:5]
	v_mov_b64_e32 v[10:11], v[4:5]
	v_mov_b64_e32 v[12:13], v[4:5]
	s_and_saveexec_b64 s[28:29], s[30:31]
	s_cbranch_execz .LBB0_314
	s_lshl_b64 s[30:31], s[26:27], 10
	v_lshl_add_u64 v[8:9], v[6:7], 0, s[30:31]
	global_load_dwordx4 v[8:11], v[8:9], off
	s_waitcnt vmcnt(0)
	v_and_b32_e32 v12, 0xffff0000, v8
	v_lshlrev_b32_e32 v13, 16, v8
	v_and_b32_e32 v8, 0xffff0000, v9
	v_lshlrev_b32_e32 v9, 16, v9
	v_and_b32_e32 v14, 0xffff0000, v10
	v_lshlrev_b32_e32 v15, 16, v10
	v_and_b32_e32 v16, 0xffff0000, v11
	v_lshlrev_b32_e32 v17, 16, v11
	v_pk_add_f32 v[12:13], v[12:13], 0 op_sel_hi:[1,0]
	v_pk_add_f32 v[10:11], v[8:9], 0 op_sel_hi:[1,0]
	v_pk_add_f32 v[8:9], v[14:15], 0 op_sel_hi:[1,0]
	v_pk_add_f32 v[14:15], v[16:17], 0 op_sel_hi:[1,0]
